# mLSTM out-phase conv staging loop: conv weights loaded twice per item instead of before every token, both tokens' LDS rows read up front
# baseline (speedup 1.0000x reference)
; DEVI float bf2f(u16 b) { return __uint_as_float(((unsigned)b) << 16); }
; DEVI unsigned cvt_pk(float lo, float hi) { f32v2_t f = {lo, hi}; bf16v2_t v = __builtin_convertvector(f, bf16v2_t); return __builtin_bit_cast(unsigned, v); }
; DEVI float siluf_(float x) { return x * __builtin_amdgcn_rcpf(1.f + __expf(-x)); }
; DEVI void mlstm_conv8_lds(const u16* raw, const float* convw, int t, int c8, int ch0, float* out) {
;     float accv[8];
; #pragma unroll
;     for (int i = 0; i < 8; ++i) accv[i] = 0.f;
; #pragma unroll
;     for (int j = 0; j < 4; ++j) { const bf16x8 x = *(const bf16x8*)(raw + (t + j) * 128 + c8);
;         const f32x4 w0 = *(const f32x4*)(convw + j * 1024 + ch0), w1 = *(const f32x4*)(convw + j * 1024 + ch0 + 4);
; #pragma unroll
;         for (int i = 0; i < 4; ++i) { accv[i] += w0[i] * bf2f((u16)x[i]); accv[4 + i] += w1[i] * bf2f((u16)x[4 + i]); } }
; #pragma unroll
;     for (int i = 0; i < 8; ++i) out[i] = siluf_(accv[i]);
; template <int KIND>
; DEVI void mix_out_phase(unsigned char* smem, const MixArgs a) {
;     ...
; #pragma unroll 2
;             for (int i = tid; i < 128 * 32; i += 512) { const int t = (i >> 4) & 127, c8 = (i & 15) * 8, isk = i >> 11; float v[8];
;                 mlstm_conv8_lds(RAW + isk * (131 * 128), a.convw, t, c8, isk * 512 + h * 128 + c8, v); const float sc = isk ? 1.f : 0.08838834764831845f;
;                 u32x4 w; w.x = cvt_pk(v[0] * sc, v[1] * sc); w.y = cvt_pk(v[2] * sc, v[3] * sc); w.z = cvt_pk(v[4] * sc, v[5] * sc); w.w = cvt_pk(v[6] * sc, v[7] * sc);
;                 *(u32x4*)((isk ? KS : QS) + t * LP + c8) = w; }
.LBB0_823:
	v_ashrrev_i32_e32 v18, 11, v22
	v_mov_b32_e32 v26, s96
	v_and_b32_e32 v25, 0x78, v23
	v_mad_i32_i24 v20, v18, s18, v26
	v_lshlrev_b32_e32 v18, 9, v18
	v_or3_b32 v18, v18, s17, v25
	v_bfe_u32 v27, v22, 4, 7
	v_ashrrev_i32_e32 v19, 31, v18
	v_lshlrev_b32_e32 v24, 1, v25
	v_lshl_add_u64 v[64:65], v[18:19], 2, s[36:37]
	v_lshlrev_b32_e32 v18, 8, v27
	v_add3_u32 v60, v20, v24, v18
	ds_read_b128 v[68:71], v60
	ds_read_b128 v[72:75], v60 offset:256
	ds_read_b128 v[76:79], v60 offset:512
	ds_read_b128 v[80:83], v60 offset:768
	ds_read_b128 v[188:191], v60 offset:8192
	ds_read_b128 v[192:195], v60 offset:8448
	ds_read_b128 v[196:199], v60 offset:8704
	ds_read_b128 v[200:203], v60 offset:8960
	v_readfirstlane_b32 s100, v22
	s_bitcmp1_b32 s100, 10
	s_cbranch_scc1 .Lcw1_skip
	v_lshl_add_u64 v[84:85], v[64:65], 0, s[26:27]
	v_lshl_add_u64 v[86:87], v[64:65], 0, s[74:75]
	v_lshl_add_u64 v[88:89], v[64:65], 0, s[38:39]
	global_load_dwordx4 v[28:31], v[64:65], off
	global_load_dwordx4 v[32:35], v[64:65], off offset:16
	global_load_dwordx4 v[36:39], v[84:85], off
	global_load_dwordx4 v[40:43], v[84:85], off offset:16
	global_load_dwordx4 v[44:47], v[86:87], off
	global_load_dwordx4 v[48:51], v[86:87], off offset:16
	global_load_dwordx4 v[52:55], v[88:89], off
	global_load_dwordx4 v[56:59], v[88:89], off offset:16
.Lcw1_skip:
	v_cmp_gt_u32_e32 vcc, s51, v22
	v_mov_b32_e32 v90, s7
	v_mov_b32_e32 v91, s84
	v_mul_u32_u24_e32 v27, 0x110, v27
	v_cndmask_b32_e32 v112, 1.0, v212, vcc
	v_cndmask_b32_e32 v61, v90, v91, vcc
	v_add3_u32 v61, v61, v27, v24
	v_cmp_lt_i32_e32 vcc, s6, v22
	v_add_u32_e32 v22, 0x400, v22
	v_add_u32_e32 v23, 0x2000, v23
	s_or_b64 s[14:15], vcc, s[14:15]
	s_waitcnt vmcnt(0) lgkmcnt(4)
	v_and_b32_e32 v109, 0xffff0000, v68
	v_lshlrev_b32_e32 v108, 16, v68
	v_pk_fma_f32 v[106:107], v[28:29], v[108:109], 0 op_sel_hi:[1,1,0]
	v_and_b32_e32 v109, 0xffff0000, v72
	v_lshlrev_b32_e32 v108, 16, v72
	v_pk_fma_f32 v[106:107], v[36:37], v[108:109], v[106:107]
	v_and_b32_e32 v109, 0xffff0000, v76
	v_lshlrev_b32_e32 v108, 16, v76
	v_pk_fma_f32 v[106:107], v[44:45], v[108:109], v[106:107]
	v_and_b32_e32 v109, 0xffff0000, v80
	v_lshlrev_b32_e32 v108, 16, v80
	v_pk_fma_f32 v[106:107], v[52:53], v[108:109], v[106:107]
	s_nop 0
	v_mul_f32_e32 v62, 0xbfb8aa3b, v106
	v_exp_f32_e32 v62, v62
	v_mul_f32_e32 v63, 0xbfb8aa3b, v107
	v_exp_f32_e32 v63, v63
	v_add_f32_e32 v62, 1.0, v62
	v_rcp_f32_e32 v110, v62
	v_add_f32_e32 v63, 1.0, v63
	v_rcp_f32_e32 v111, v63
	s_nop 0
	v_pk_mul_f32 v[106:107], v[106:107], v[110:111]
	s_nop 0
	v_pk_mul_f32 v[106:107], v[112:113], v[106:107] op_sel_hi:[0,1]
	s_nop 0
	v_cvt_pk_bf16_f32 v18, v106, v107
	v_and_b32_e32 v109, 0xffff0000, v69
	v_lshlrev_b32_e32 v108, 16, v69
	v_pk_fma_f32 v[106:107], v[30:31], v[108:109], 0 op_sel_hi:[1,1,0]
	v_and_b32_e32 v109, 0xffff0000, v73
	v_lshlrev_b32_e32 v108, 16, v73
	v_pk_fma_f32 v[106:107], v[38:39], v[108:109], v[106:107]
	v_and_b32_e32 v109, 0xffff0000, v77
	v_lshlrev_b32_e32 v108, 16, v77
	v_pk_fma_f32 v[106:107], v[46:47], v[108:109], v[106:107]
	v_and_b32_e32 v109, 0xffff0000, v81
	v_lshlrev_b32_e32 v108, 16, v81
	v_pk_fma_f32 v[106:107], v[54:55], v[108:109], v[106:107]
	s_nop 0
	v_mul_f32_e32 v62, 0xbfb8aa3b, v106
	v_exp_f32_e32 v62, v62
	v_mul_f32_e32 v63, 0xbfb8aa3b, v107
	v_exp_f32_e32 v63, v63
	v_add_f32_e32 v62, 1.0, v62
	v_rcp_f32_e32 v110, v62
	v_add_f32_e32 v63, 1.0, v63
	v_rcp_f32_e32 v111, v63
	s_nop 0
	v_pk_mul_f32 v[106:107], v[106:107], v[110:111]
	s_nop 0
	v_pk_mul_f32 v[106:107], v[112:113], v[106:107] op_sel_hi:[0,1]
	s_nop 0
	v_cvt_pk_bf16_f32 v19, v106, v107
	v_and_b32_e32 v109, 0xffff0000, v70
	v_lshlrev_b32_e32 v108, 16, v70
	v_pk_fma_f32 v[106:107], v[32:33], v[108:109], 0 op_sel_hi:[1,1,0]
	v_and_b32_e32 v109, 0xffff0000, v74
	v_lshlrev_b32_e32 v108, 16, v74
	v_pk_fma_f32 v[106:107], v[40:41], v[108:109], v[106:107]
	v_and_b32_e32 v109, 0xffff0000, v78
	v_lshlrev_b32_e32 v108, 16, v78
	v_pk_fma_f32 v[106:107], v[48:49], v[108:109], v[106:107]
	v_and_b32_e32 v109, 0xffff0000, v82
	v_lshlrev_b32_e32 v108, 16, v82
	v_pk_fma_f32 v[106:107], v[56:57], v[108:109], v[106:107]
	s_nop 0
	v_mul_f32_e32 v62, 0xbfb8aa3b, v106
	v_exp_f32_e32 v62, v62
	v_mul_f32_e32 v63, 0xbfb8aa3b, v107
	v_exp_f32_e32 v63, v63
	v_add_f32_e32 v62, 1.0, v62
	v_rcp_f32_e32 v110, v62
	v_add_f32_e32 v63, 1.0, v63
	v_rcp_f32_e32 v111, v63
	s_nop 0
	v_pk_mul_f32 v[106:107], v[106:107], v[110:111]
	s_nop 0
	v_pk_mul_f32 v[106:107], v[112:113], v[106:107] op_sel_hi:[0,1]
	s_nop 0
	v_cvt_pk_bf16_f32 v20, v106, v107
	v_and_b32_e32 v109, 0xffff0000, v71
	v_lshlrev_b32_e32 v108, 16, v71
	v_pk_fma_f32 v[106:107], v[34:35], v[108:109], 0 op_sel_hi:[1,1,0]
	v_and_b32_e32 v109, 0xffff0000, v75
	v_lshlrev_b32_e32 v108, 16, v75
	v_pk_fma_f32 v[106:107], v[42:43], v[108:109], v[106:107]
	v_and_b32_e32 v109, 0xffff0000, v79
	v_lshlrev_b32_e32 v108, 16, v79
	v_pk_fma_f32 v[106:107], v[50:51], v[108:109], v[106:107]
	v_and_b32_e32 v109, 0xffff0000, v83
	v_lshlrev_b32_e32 v108, 16, v83
	v_pk_fma_f32 v[106:107], v[58:59], v[108:109], v[106:107]
	s_nop 0
	v_mul_f32_e32 v62, 0xbfb8aa3b, v106
	v_exp_f32_e32 v62, v62
	v_mul_f32_e32 v63, 0xbfb8aa3b, v107
	v_exp_f32_e32 v63, v63
	v_add_f32_e32 v62, 1.0, v62
	v_rcp_f32_e32 v110, v62
	v_add_f32_e32 v63, 1.0, v63
	v_rcp_f32_e32 v111, v63
	s_nop 0
	v_pk_mul_f32 v[106:107], v[106:107], v[110:111]
	s_nop 0
	v_pk_mul_f32 v[106:107], v[112:113], v[106:107] op_sel_hi:[0,1]
	s_nop 0
	v_cvt_pk_bf16_f32 v21, v106, v107
	ds_write_b128 v61, v[18:21]
	s_waitcnt lgkmcnt(1)
; DEVI float bf2f(u16 b) { return __uint_as_float(((unsigned)b) << 16); }
; DEVI unsigned cvt_pk(float lo, float hi) { f32v2_t f = {lo, hi}; bf16v2_t v = __builtin_convertvector(f, bf16v2_t); return __builtin_bit_cast(unsigned, v); }
; DEVI float siluf_(float x) { return x * __builtin_amdgcn_rcpf(1.f + __expf(-x)); }
; DEVI void mlstm_conv8_lds(const u16* raw, const float* convw, int t, int c8, int ch0, float* out) {
;     float accv[8];
; #pragma unroll
;     for (int i = 0; i < 8; ++i) accv[i] = 0.f;
; #pragma unroll
;     for (int j = 0; j < 4; ++j) { const bf16x8 x = *(const bf16x8*)(raw + (t + j) * 128 + c8);
;         const f32x4 w0 = *(const f32x4*)(convw + j * 1024 + ch0), w1 = *(const f32x4*)(convw + j * 1024 + ch0 + 4);
; #pragma unroll
;         for (int i = 0; i < 4; ++i) { accv[i] += w0[i] * bf2f((u16)x[i]); accv[4 + i] += w1[i] * bf2f((u16)x[4 + i]); } }
; #pragma unroll
;     for (int i = 0; i < 8; ++i) out[i] = siluf_(accv[i]);
; template <int KIND>
; DEVI void mix_out_phase(unsigned char* smem, const MixArgs a) {
;     ...
; #pragma unroll 2
;             for (int i = tid; i < 128 * 32; i += 512) { const int t = (i >> 4) & 127, c8 = (i & 15) * 8, isk = i >> 11; float v[8];
;                 mlstm_conv8_lds(RAW + isk * (131 * 128), a.convw, t, c8, isk * 512 + h * 128 + c8, v); const float sc = isk ? 1.f : 0.08838834764831845f;
;                 u32x4 w; w.x = cvt_pk(v[0] * sc, v[1] * sc); w.y = cvt_pk(v[2] * sc, v[3] * sc); w.z = cvt_pk(v[4] * sc, v[5] * sc); w.w = cvt_pk(v[6] * sc, v[7] * sc);
;                 *(u32x4*)((isk ? KS : QS) + t * LP + c8) = w; }
	v_and_b32_e32 v109, 0xffff0000, v188
	v_lshlrev_b32_e32 v108, 16, v188
	v_pk_fma_f32 v[106:107], v[28:29], v[108:109], 0 op_sel_hi:[1,1,0]
	v_and_b32_e32 v109, 0xffff0000, v192
	v_lshlrev_b32_e32 v108, 16, v192
	v_pk_fma_f32 v[106:107], v[36:37], v[108:109], v[106:107]
	v_and_b32_e32 v109, 0xffff0000, v196
	v_lshlrev_b32_e32 v108, 16, v196
	v_pk_fma_f32 v[106:107], v[44:45], v[108:109], v[106:107]
	v_and_b32_e32 v109, 0xffff0000, v200
	v_lshlrev_b32_e32 v108, 16, v200
	v_pk_fma_f32 v[106:107], v[52:53], v[108:109], v[106:107]
	s_nop 0
	v_mul_f32_e32 v62, 0xbfb8aa3b, v106
	v_exp_f32_e32 v62, v62
	v_mul_f32_e32 v63, 0xbfb8aa3b, v107
	v_exp_f32_e32 v63, v63
	v_add_f32_e32 v62, 1.0, v62
	v_rcp_f32_e32 v110, v62
	v_add_f32_e32 v63, 1.0, v63
	v_rcp_f32_e32 v111, v63
	s_nop 0
	v_pk_mul_f32 v[106:107], v[106:107], v[110:111]
	s_nop 0
	v_pk_mul_f32 v[106:107], v[112:113], v[106:107] op_sel_hi:[0,1]
	s_nop 0
	v_cvt_pk_bf16_f32 v102, v106, v107
	v_and_b32_e32 v109, 0xffff0000, v189
	v_lshlrev_b32_e32 v108, 16, v189
	v_pk_fma_f32 v[106:107], v[30:31], v[108:109], 0 op_sel_hi:[1,1,0]
	v_and_b32_e32 v109, 0xffff0000, v193
	v_lshlrev_b32_e32 v108, 16, v193
	v_pk_fma_f32 v[106:107], v[38:39], v[108:109], v[106:107]
	v_and_b32_e32 v109, 0xffff0000, v197
	v_lshlrev_b32_e32 v108, 16, v197
	v_pk_fma_f32 v[106:107], v[46:47], v[108:109], v[106:107]
	v_and_b32_e32 v109, 0xffff0000, v201
	v_lshlrev_b32_e32 v108, 16, v201
	v_pk_fma_f32 v[106:107], v[54:55], v[108:109], v[106:107]
	s_nop 0
	v_mul_f32_e32 v62, 0xbfb8aa3b, v106
	v_exp_f32_e32 v62, v62
	v_mul_f32_e32 v63, 0xbfb8aa3b, v107
	v_exp_f32_e32 v63, v63
	v_add_f32_e32 v62, 1.0, v62
	v_rcp_f32_e32 v110, v62
	v_add_f32_e32 v63, 1.0, v63
	v_rcp_f32_e32 v111, v63
	s_nop 0
	v_pk_mul_f32 v[106:107], v[106:107], v[110:111]
	s_nop 0
	v_pk_mul_f32 v[106:107], v[112:113], v[106:107] op_sel_hi:[0,1]
	s_nop 0
	v_cvt_pk_bf16_f32 v103, v106, v107
	v_and_b32_e32 v109, 0xffff0000, v190
	v_lshlrev_b32_e32 v108, 16, v190
	v_pk_fma_f32 v[106:107], v[32:33], v[108:109], 0 op_sel_hi:[1,1,0]
	v_and_b32_e32 v109, 0xffff0000, v194
	v_lshlrev_b32_e32 v108, 16, v194
	v_pk_fma_f32 v[106:107], v[40:41], v[108:109], v[106:107]
	v_and_b32_e32 v109, 0xffff0000, v198
	v_lshlrev_b32_e32 v108, 16, v198
	v_pk_fma_f32 v[106:107], v[48:49], v[108:109], v[106:107]
	v_and_b32_e32 v109, 0xffff0000, v202
	v_lshlrev_b32_e32 v108, 16, v202
	v_pk_fma_f32 v[106:107], v[56:57], v[108:109], v[106:107]
	s_nop 0
	v_mul_f32_e32 v62, 0xbfb8aa3b, v106
	v_exp_f32_e32 v62, v62
	v_mul_f32_e32 v63, 0xbfb8aa3b, v107
	v_exp_f32_e32 v63, v63
	v_add_f32_e32 v62, 1.0, v62
	v_rcp_f32_e32 v110, v62
	v_add_f32_e32 v63, 1.0, v63
	v_rcp_f32_e32 v111, v63
	s_nop 0
	v_pk_mul_f32 v[106:107], v[106:107], v[110:111]
	s_nop 0
	v_pk_mul_f32 v[106:107], v[112:113], v[106:107] op_sel_hi:[0,1]
	s_nop 0
	v_cvt_pk_bf16_f32 v104, v106, v107
	v_and_b32_e32 v109, 0xffff0000, v191
	v_lshlrev_b32_e32 v108, 16, v191
	v_pk_fma_f32 v[106:107], v[34:35], v[108:109], 0 op_sel_hi:[1,1,0]
	v_and_b32_e32 v109, 0xffff0000, v195
	v_lshlrev_b32_e32 v108, 16, v195
	v_pk_fma_f32 v[106:107], v[42:43], v[108:109], v[106:107]
	v_and_b32_e32 v109, 0xffff0000, v199
	v_lshlrev_b32_e32 v108, 16, v199
	v_pk_fma_f32 v[106:107], v[50:51], v[108:109], v[106:107]
	v_and_b32_e32 v109, 0xffff0000, v203
	v_lshlrev_b32_e32 v108, 16, v203
	v_pk_fma_f32 v[106:107], v[58:59], v[108:109], v[106:107]
	s_nop 0
	v_mul_f32_e32 v62, 0xbfb8aa3b, v106
	v_exp_f32_e32 v62, v62
	v_mul_f32_e32 v63, 0xbfb8aa3b, v107
	v_exp_f32_e32 v63, v63
	v_add_f32_e32 v62, 1.0, v62
	v_rcp_f32_e32 v110, v62
	v_add_f32_e32 v63, 1.0, v63
	v_rcp_f32_e32 v111, v63
	s_nop 0
	v_pk_mul_f32 v[106:107], v[106:107], v[110:111]
	s_nop 0
	v_pk_mul_f32 v[106:107], v[112:113], v[106:107] op_sel_hi:[0,1]
	s_nop 0
	v_cvt_pk_bf16_f32 v105, v106, v107
	ds_write_b128 v61, v[102:105] offset:8704
	s_andn2_b64 exec, exec, s[14:15]
	s_cbranch_execnz .LBB0_823
